# k54: k42 + explicit completion counter for the units run by the prompt-chain workgroups (side-barrier leaders wait for it before their L2 write-back at steps 4 and 13)
# baseline (speedup 1.0000x reference)
; __device__ __forceinline__ unsigned xb_ld(unsigned* p)              { return __hip_atomic_load(p, __ATOMIC_RELAXED, __HIP_MEMORY_SCOPE_AGENT); }
; __device__ __forceinline__ unsigned xb_add(unsigned* p, unsigned v) { return __hip_atomic_fetch_add(p, v, __ATOMIC_RELAXED, __HIP_MEMORY_SCOPE_AGENT); }
; #define XB_SPIN(cond, bar) do { unsigned _sp = 0; while (cond) { __builtin_amdgcn_s_sleep(1); \
;     if ((++_sp & 255u) == 0u) { if (xb_ld(&(bar)[XB_TMO])) break; if (_sp > XB_SPIN_CAP) { atomicAdd(&(bar)[XB_TMO], 1u); break; } } } } while (0)
; __device__ __forceinline__ void xcd_barrier(const XcdBarrier& b) {
;     asm volatile("s_waitcnt vmcnt(0)" ::: "memory");
;     __syncthreads();
;     if (threadIdx.x == 0) {
;         unsigned* bar = b.bar;
;         __builtin_amdgcn_s_waitcnt(0);
;         unsigned nloc = b.st[0], nx = b.st[1];
;         if (nloc == 0u) { xcd_barrier_complete(bar, b.x, b.gsz, nloc, nx); b.st[0] = nloc; b.st[1] = nx; }
;         const unsigned old = xb_add(&bar[XB_XSUB(b.x)], 1u);
;         const unsigned gen = old / nloc;
;         if (old + 1u == (gen + 1u) * nloc) {
;             __builtin_amdgcn_fence(__ATOMIC_RELEASE, "agent");
;             asm volatile("s_waitcnt vmcnt(0)" ::: "memory");
;             const unsigned og = xb_add(&bar[XB_TOP], 1u);
;             const unsigned tg = og / nx;
;             if (og + 1u == (tg + 1u) * nx) xb_add(&bar[XB_TOPGEN], 1u);
;             else XB_SPIN(xb_ld(&bar[XB_TOPGEN]) == tg, bar);
;             __builtin_amdgcn_fence(__ATOMIC_ACQUIRE, "agent");
;             xb_add(&bar[XB_XGEN(b.x)], 1u);
.LBB0_186:
	s_andn2_saveexec_b64 s[6:7], s[6:7]
	s_cbranch_execz .LBB0_206
	s_mov_b64 s[6:7], exec
	s_cmp_eq_u32 s3, 4
	s_cbranch_scc1 .Lcw_l0
	s_cmp_eq_u32 s3, 13
	s_cbranch_scc0 .Lcw_done
	s_movk_i32 s8, 0x200
	s_add_u32 s10, s94, 0x8040
	s_branch .Lcw_go
.Lcw_l0:
	s_movk_i32 s8, 0x100
	s_add_u32 s10, s94, 0x8000
.Lcw_go:
	s_addc_u32 s11, s95, 0
	s_mov_b32 s9, 0
.Lcw_spin:
	global_load_dword v1, v3, s[10:11] sc1
	s_waitcnt vmcnt(0)
	v_cmp_le_u32_e32 vcc, s8, v1
	s_cbranch_vccnz .Lcw_done
	s_sleep 1
	s_add_i32 s9, s9, 1
	s_cmp_lt_u32 s9, 0x1000
	s_cbranch_scc1 .Lcw_spin
.Lcw_done:
	buffer_wbl2 sc1
	s_waitcnt lgkmcnt(0)
	s_waitcnt vmcnt(0)
	v_mbcnt_lo_u32_b32 v1, s6, 0
	v_mbcnt_hi_u32_b32 v1, s7, v1
	v_cmp_eq_u32_e32 vcc, 0, v1
	s_and_saveexec_b64 s[8:9], vcc
	s_cbranch_execz .LBB0_189
	s_bcnt1_i32_b64 s6, s[6:7]
	v_mov_b32_e32 v2, s6
	v_readlane_b32 s6, v251, 48
	v_readlane_b32 s7, v251, 49
	s_nop 4
	global_atomic_add v2, v3, v2, s[6:7] sc0

; __device__ __forceinline__ void mixer_layer0(Frame& F) {
;     const float* rot = (const float*)(F.ws + WS_ROT);
;     int bid = blockIdx.x; asm volatile("" : "+s"(bid));
;     if (bid < 64) { const int u = bid, ty = u >> 5, bh = u & 31; if (ty == 0) mix_sg_unit<0>(F, bh >> 2, bh & 3, 0, rot); else mix_sg_unit<1>(F, bh >> 2, bh & 3, 0, rot); return; }
; #pragma unroll 1
;     for (int u = bid - 64; u < 1024 + 8; u += F.G - 64) {
;         int ty, bh, mode;
;         if (u < 1024) { ty = u >> 9; bh = u & 511; mode = 1; } else { ty = (u - 1024) >> 2; bh = (u - 1024) & 3; mode = 2; }
;         if (ty == 0) mix_sg_unit<0>(F, bh >> 2, bh & 3, mode, rot); else mix_sg_unit<1>(F, bh >> 2, bh & 3, mode, rot);
;     }
.LBB0_766:
	s_cmp_gt_i32 s78, 63
	s_cbranch_scc1 .Lsig0_skip
	s_waitcnt vmcnt(0)
	s_add_u32 s100, s94, 0x8000
	s_addc_u32 s101, s95, 0
	s_mov_b64 s[98:99], exec
	s_mov_b64 exec, 1
	global_atomic_add v3, v210, s[100:101]
	s_mov_b64 exec, s[98:99]

; __device__ __forceinline__ void mixer_layer1(Frame& F) {
;     int bid = blockIdx.x; asm volatile("" : "+s"(bid));
;     if (bid < 64) { mix_hg_unit(F, bid >> 3, bid & 7, 0); return; }
; #pragma unroll 1
;     for (int u = bid - 64; u < 1024 + 8; u += F.G - 64) {
;         if (u < 1024) mix_hg_unit(F, u >> 3, u & 7, 1); else mix_hg_unit(F, 0, u - 1024, 2);
;     }
.LBB0_874:
	s_cmp_gt_i32 s0, 63
	s_cbranch_scc1 .Lsig1_skip
	s_waitcnt vmcnt(0)
	s_add_u32 s100, s94, 0x8040
	s_addc_u32 s101, s95, 0
	s_mov_b64 s[98:99], exec
	s_mov_b64 exec, 1
	global_atomic_add v3, v210, s[100:101]
	s_mov_b64 exec, s[98:99]
